# previous + retention scan: LDS fragment reads of the inter-chunk and score MFMA sections pipelined ahead of the MFMAs
# speedup vs baseline: 1.0588x; 1.0101x over previous
; #define MFMA(a, b, c) __builtin_amdgcn_mfma_f32_32x32x16_bf16((a), (b), (c), 0, 0, 0)
; DI int crow(int r, int hi) { return (r & 3) + 8 * (r >> 2) + 4 * hi; }
; template <bool ML>
; DI void scan_block(const Params& p, int sitem, char* smem) {
;     ...
;         const bfu* k0 = kS + l32 * LQ + hi * 8; const bfu* kx = k0 + sbx * 32 * LQ;
;         const bfu* q0 = qS + l32 * LQ + hi * 8; const bfu* qx = q0 + tbx * 32 * LQ;
; #pragma unroll 2
;         for (int ks = 0; ks < 8; ++ks) {
;           sd0 = MFMA(ld8(k0 + ks * 16), ld8(q0 + ks * 16), sd0);
;           sx = MFMA(ld8(kx + ks * 16), ld8(qx + ks * 16), sx);
;         }
;         const float sBx = tbx ? sB1 : sB0;
; #pragma unroll
;         for (int r = 0; r < 16; ++r) {
;           const int sl = crow(r, hi);
;           const bool valid = dir == 0 ? sl <= l32 : sl >= l32;
;           float w0, wx;
;           if (ML) { w0 = __expf(sB0 + wsm[64 + sl]); wx = __expf(sBx + wsm[64 + sbx * 32 + sl]); }
;           else { w0 = sB0 * wsm[64 + sl]; wx = sBx * wsm[64 + sbx * 32 + sl]; }
;           sd0[r] = valid ? sd0[r] * w0 : 0.f; sx[r] *= wx;
.LBB0_1464:
	v_add_u32_e32 v205, s46, v243
	v_add_u32_e32 v206, s47, v243
	ds_read_b128 v[244:247], v243 offset:17408
	ds_read_b128 v[248:251], v243
	ds_read_b128 v[210:213], v205 offset:17408
	ds_read_b128 v[216:219], v206
	s_waitcnt lgkmcnt(2)
	v_mfma_f32_32x32x16_bf16 v[112:127], v[244:247], v[248:251], v[112:127]
	ds_read_b128 v[244:247], v243 offset:17440
	ds_read_b128 v[248:251], v243 offset:32
	s_waitcnt lgkmcnt(2)
	v_mfma_f32_32x32x16_bf16 v[96:111], v[210:213], v[216:219], v[96:111]
	ds_read_b128 v[210:213], v205 offset:17440
	ds_read_b128 v[216:219], v206 offset:32
	s_waitcnt lgkmcnt(2)
	v_mfma_f32_32x32x16_bf16 v[112:127], v[244:247], v[248:251], v[112:127]
	ds_read_b128 v[244:247], v243 offset:17472
	ds_read_b128 v[248:251], v243 offset:64
	s_waitcnt lgkmcnt(2)
	v_mfma_f32_32x32x16_bf16 v[96:111], v[210:213], v[216:219], v[96:111]
	ds_read_b128 v[210:213], v205 offset:17472
	ds_read_b128 v[216:219], v206 offset:64
	s_waitcnt lgkmcnt(2)
	v_mfma_f32_32x32x16_bf16 v[112:127], v[244:247], v[248:251], v[112:127]
	ds_read_b128 v[244:247], v243 offset:17504
	ds_read_b128 v[248:251], v243 offset:96
	s_waitcnt lgkmcnt(2)
	v_mfma_f32_32x32x16_bf16 v[96:111], v[210:213], v[216:219], v[96:111]
	ds_read_b128 v[210:213], v205 offset:17504
	ds_read_b128 v[216:219], v206 offset:96
	s_waitcnt lgkmcnt(2)
	v_mfma_f32_32x32x16_bf16 v[112:127], v[244:247], v[248:251], v[112:127]
	ds_read_b128 v[244:247], v243 offset:17536
	ds_read_b128 v[248:251], v243 offset:128
	s_waitcnt lgkmcnt(2)
	v_mfma_f32_32x32x16_bf16 v[96:111], v[210:213], v[216:219], v[96:111]
	ds_read_b128 v[210:213], v205 offset:17536
	ds_read_b128 v[216:219], v206 offset:128
	s_waitcnt lgkmcnt(2)
	v_mfma_f32_32x32x16_bf16 v[112:127], v[244:247], v[248:251], v[112:127]
	ds_read_b128 v[244:247], v243 offset:17568
	ds_read_b128 v[248:251], v243 offset:160
	s_waitcnt lgkmcnt(2)
	v_mfma_f32_32x32x16_bf16 v[96:111], v[210:213], v[216:219], v[96:111]
	ds_read_b128 v[210:213], v205 offset:17568
	ds_read_b128 v[216:219], v206 offset:160
	s_waitcnt lgkmcnt(2)
	v_mfma_f32_32x32x16_bf16 v[112:127], v[244:247], v[248:251], v[112:127]
	ds_read_b128 v[244:247], v243 offset:17600
	ds_read_b128 v[248:251], v243 offset:192
	s_waitcnt lgkmcnt(2)
	v_mfma_f32_32x32x16_bf16 v[96:111], v[210:213], v[216:219], v[96:111]
	ds_read_b128 v[210:213], v205 offset:17600
	ds_read_b128 v[216:219], v206 offset:192
	s_waitcnt lgkmcnt(2)
	v_mfma_f32_32x32x16_bf16 v[112:127], v[244:247], v[248:251], v[112:127]
	ds_read_b128 v[244:247], v243 offset:17632
	ds_read_b128 v[248:251], v243 offset:224
	s_waitcnt lgkmcnt(2)
	v_mfma_f32_32x32x16_bf16 v[96:111], v[210:213], v[216:219], v[96:111]
	ds_read_b128 v[210:213], v205 offset:17632
	ds_read_b128 v[216:219], v206 offset:224
	s_waitcnt lgkmcnt(2)
	v_mfma_f32_32x32x16_bf16 v[112:127], v[244:247], v[248:251], v[112:127]
	s_waitcnt lgkmcnt(0)
	v_mfma_f32_32x32x16_bf16 v[96:111], v[210:213], v[216:219], v[96:111]
	ds_read_b32 v249, v224 offset:256
	v_mov_b32_e32 v243, 0
	v_mov_b32_e32 v244, 0
	s_and_saveexec_b64 s[40:41], s[6:7]
	s_cbranch_execz .LBB0_1467
	ds_read_b32 v205, v169 offset:256
	s_waitcnt lgkmcnt(0)
	v_mul_f32_e32 v205, v192, v205
	v_mul_f32_e32 v244, v112, v205

; #define MFMA(a, b, c) __builtin_amdgcn_mfma_f32_32x32x16_bf16((a), (b), (c), 0, 0, 0)
; DI int crow(int r, int hi) { return (r & 3) + 8 * (r >> 2) + 4 * hi; }
; template <bool ML>
; DI void scan_block(const Params& p, int sitem, char* smem) {
;     ...
;         for (int r = 0; r < 16; ++r) { sa[r] = 0.f; sb_[r] = 0.f; }
;         const bfu* k1 = kS + (32 + l32) * LQ + hi * 8; const bfu* q1 = qS + (32 + l32) * LQ + hi * 8;
; #pragma unroll 2
;         for (int ks = 0; ks < 8; ks += 2) {
;           sa = MFMA(ld8(k1 + ks * 16), ld8(q1 + ks * 16), sa);
;           sb_ = MFMA(ld8(k1 + ks * 16 + 16), ld8(q1 + ks * 16 + 16), sb_);
;         }
; #pragma unroll
;         for (int r = 0; r < 16; ++r) {
;           const int sl = crow(r, hi);
;           const bool valid = dir == 0 ? sl <= l32 : sl >= l32;
;           float w1;
;           if (ML) w1 = __expf(sB1 + wsm[96 + sl]);
;           else w1 = sB1 * wsm[96 + sl];
;           sa[r] = valid ? (sa[r] + sb_[r]) * w1 : 0.f;
.LBB0_1502:
	ds_read_b128 v[244:247], v190 offset:17408
	ds_read_b128 v[248:251], v190
	ds_read_b128 v[210:213], v190 offset:17440
	ds_read_b128 v[216:219], v190 offset:32
	s_waitcnt lgkmcnt(2)
	v_mfma_f32_32x32x16_bf16 v[112:127], v[244:247], v[248:251], v[112:127]
	ds_read_b128 v[244:247], v190 offset:17472
	ds_read_b128 v[248:251], v190 offset:64
	s_waitcnt lgkmcnt(2)
	v_mfma_f32_32x32x16_bf16 v[96:111], v[210:213], v[216:219], v[96:111]
	ds_read_b128 v[210:213], v190 offset:17504
	ds_read_b128 v[216:219], v190 offset:96
	s_waitcnt lgkmcnt(2)
	v_mfma_f32_32x32x16_bf16 v[112:127], v[244:247], v[248:251], v[112:127]
	ds_read_b128 v[244:247], v190 offset:17536
	ds_read_b128 v[248:251], v190 offset:128
	s_waitcnt lgkmcnt(2)
	v_mfma_f32_32x32x16_bf16 v[96:111], v[210:213], v[216:219], v[96:111]
	ds_read_b128 v[210:213], v190 offset:17568
	ds_read_b128 v[216:219], v190 offset:160
	s_waitcnt lgkmcnt(2)
	v_mfma_f32_32x32x16_bf16 v[112:127], v[244:247], v[248:251], v[112:127]
	ds_read_b128 v[244:247], v190 offset:17600
	ds_read_b128 v[248:251], v190 offset:192
	s_waitcnt lgkmcnt(2)
	v_mfma_f32_32x32x16_bf16 v[96:111], v[210:213], v[216:219], v[96:111]
	ds_read_b128 v[210:213], v190 offset:17632
	ds_read_b128 v[216:219], v190 offset:224
	s_waitcnt lgkmcnt(2)
	v_mfma_f32_32x32x16_bf16 v[112:127], v[244:247], v[248:251], v[112:127]
	s_waitcnt lgkmcnt(0)
	v_mfma_f32_32x32x16_bf16 v[96:111], v[210:213], v[216:219], v[96:111]
	v_mov_b32_e32 v190, 0
	v_mov_b32_e32 v193, 0
	s_and_saveexec_b64 s[40:41], s[6:7]
	s_cbranch_execz .LBB0_1505
	s_nop 6
	v_add_f32_e32 v96, v112, v96
	ds_read_b32 v112, v169 offset:384
	s_waitcnt lgkmcnt(0)
	v_mul_f32_e32 v112, v242, v112
	v_mul_f32_e32 v193, v96, v112
